# S5: 3-ahead u prefetch with alternating register sets
# baseline (speedup 1.0000x reference)
.LBB0_98:
	s_or_b64 exec, exec, s[2:3]
	v_or_b32_e32 v0, v2, v204
	v_lshlrev_b64 v[8:9], 12, v[0:1]
	s_mov_b64 s[2:3], 0x1000
	v_lshlrev_b64 v[6:7], 8, v[0:1]
	v_lshl_add_u64 v[8:9], v[8:9], 0, s[2:3]
	v_cndmask_b32_e64 v7, v9, v7, s[44:45]
	v_cndmask_b32_e64 v6, v8, v6, s[44:45]
	v_readlane_b32 s4, v252, 48
	v_lshlrev_b32_e32 v4, 4, v4
	v_lshlrev_b64 v[6:7], 12, v[6:7]
	v_readlane_b32 s18, v252, 62
	v_readlane_b32 s19, v252, 63
	v_ashrrev_i32_e32 v5, 31, v4
	v_add_u32_e32 v0, -16, v3
	v_lshl_add_u64 v[6:7], s[18:19], 0, v[6:7]
	v_lshlrev_b64 v[12:13], 2, v[4:5]
	v_cndmask_b32_e64 v0, v0, 0, s[40:41]
	v_lshl_add_u64 v[4:5], v[6:7], 0, v[12:13]
	v_mov_b32_e32 v149, v1
	v_or_b32_e32 v0, v0, v205
	v_lshl_add_u64 v[156:157], v[4:5], 0, v[148:149]
	v_lshlrev_b64 v[4:5], 12, v[0:1]
	v_subrev_u32_e32 v0, 32, v3
	v_cndmask_b32_e64 v0, v0, 16, s[40:41]
	v_or_b32_e32 v0, v0, v205
	s_waitcnt vmcnt(12)
	v_lshlrev_b64 v[14:15], 12, v[0:1]
	v_lshl_add_u64 v[8:9], v[156:157], 0, v[4:5]
	v_lshl_add_u64 v[14:15], v[156:157], 0, v[14:15]
	global_load_dwordx4 v[4:7], v[8:9], off offset:16
	s_nop 0
	global_load_dwordx4 v[8:11], v[8:9], off
	s_nop 0
	global_load_dwordx4 v[98:101], v[14:15], off offset:16
	global_load_dwordx4 v[102:105], v[14:15], off
	v_lshrrev_b32_e32 v149, 4, v3
	v_subrev_u32_e32 v210, 48, v3
	v_mov_b32_e32 v3, v1
	v_lshlrev_b64 v[14:15], 12, v[2:3]
	v_lshl_add_u64 v[162:163], v[146:147], 0, v[12:13]
	v_lshlrev_b64 v[12:13], 8, v[2:3]
	v_or_b32_e32 v0, 0x1000, v14
	v_cndmask_b32_e64 v164, v0, v12, s[44:45]
	v_or_b32_e32 v0, 1, v2
	v_cndmask_b32_e64 v165, v15, v13, s[44:45]
	v_lshlrev_b64 v[12:13], 12, v[0:1]
	v_lshlrev_b64 v[2:3], 8, v[0:1]
	v_lshl_add_u64 v[12:13], v[12:13], 0, s[2:3]
	v_cndmask_b32_e64 v167, v13, v3, s[44:45]
	v_cndmask_b32_e64 v166, v12, v2, s[44:45]
	v_mov_b32_e32 v2, v1
	v_mov_b32_e32 v3, v1
	v_mov_b32_e32 v0, v1
	v_mov_b64_e32 v[108:109], v[2:3]
	v_mov_b64_e32 v[112:113], v[2:3]
	s_waitcnt vmcnt(5)
	v_pk_mov_b32 v[158:159], v[152:153], v[152:153] op_sel:[1,0]
	s_waitcnt vmcnt(4)
	v_pk_mov_b32 v[160:161], v[154:155], v[154:155] op_sel:[1,0]
	s_mov_b32 s28, 0
	s_mov_b32 s34, 32
	v_mov_b32_e32 v168, v152
	v_mov_b32_e32 v169, v152
	v_mov_b32_e32 v170, v153
	v_mov_b32_e32 v171, v153
	v_mov_b32_e32 v172, v154
	v_mov_b32_e32 v173, v154
	v_mov_b32_e32 v174, v155
	v_mov_b32_e32 v175, v155
	s_mov_b64 s[2:3], 0
	v_mov_b64_e32 v[106:107], v[0:1]
	v_mov_b64_e32 v[110:111], v[0:1]
	v_readlane_b32 s5, v252, 49
	v_readlane_b32 s6, v252, 50
	v_readlane_b32 s7, v252, 51
	v_readlane_b32 s8, v252, 52
	v_readlane_b32 s9, v252, 53
	v_readlane_b32 s10, v252, 54
	v_readlane_b32 s11, v252, 55
	v_readlane_b32 s12, v252, 56
	v_readlane_b32 s13, v252, 57
	v_readlane_b32 s14, v252, 58
	v_readlane_b32 s15, v252, 59
	v_readlane_b32 s16, v252, 60
	v_readlane_b32 s17, v252, 61
	v_mov_b32_e32 v0, s34
	v_cndmask_b32_e64 v0, v210, v0, s[40:41]
	v_or_b32_e32 v2, v0, v205
	v_ashrrev_i32_e32 v3, 31, v2
	v_lshlrev_b64 v[2:3], 12, v[2:3]
	v_lshl_add_u64 v[2:3], v[156:157], 0, v[2:3]
	global_load_dwordx4 v[110:113], v[2:3], off offset:16
	global_load_dwordx4 v[106:109], v[2:3], off
	v_mov_b32_e32 v214, 0
	v_mov_b32_e32 v215, 0
	v_mov_b32_e32 v216, 0
	v_mov_b32_e32 v217, 0
	v_mov_b32_e32 v218, 0
	v_mov_b32_e32 v219, 0
	v_mov_b32_e32 v220, 0
	v_mov_b32_e32 v221, 0
	s_waitcnt vmcnt(4)
	s_branch .LBB0_100
.LBB0_99:
	s_or_b64 exec, exec, s[20:21]
	s_sub_i32 s20, s34, 32
	v_add_u32_e32 v0, 32, v210
	v_mov_b32_e32 v2, s20
	v_cndmask_b32_e64 v0, v0, v2, s[40:41]
	s_waitcnt lgkmcnt(0)
	ds_read_b128 v[14:17], v208
	ds_read_b128 v[30:33], v208 offset:4352
	ds_read_b128 v[18:21], v208 offset:64
	ds_read_b128 v[34:37], v208 offset:4416
	ds_read_b128 v[22:25], v208 offset:128
	ds_read_b128 v[38:41], v208 offset:4480
	ds_read_b128 v[26:29], v208 offset:192
	ds_read_b128 v[42:45], v208 offset:4544
	s_movk_i32 s20, 0x3000
	s_add_i32 s28, s28, 1
	s_add_i32 s34, s34, 16
	v_add_u32_e32 v210, -16, v210
	v_mov_b32_e32 v182, v179
	v_mov_b32_e32 v180, v177
	s_waitcnt lgkmcnt(6)
	v_mfma_f32_16x16x32_bf16 v[2:5], v[14:17], v[82:85], 0
	v_mfma_f32_16x16x32_bf16 v[6:9], v[30:33], v[82:85], 0
	s_waitcnt lgkmcnt(4)
	v_mfma_f32_16x16x32_bf16 v[2:5], v[18:21], v[86:89], v[2:5]
	v_mfma_f32_16x16x32_bf16 v[6:9], v[34:37], v[86:89], v[6:9]
	s_waitcnt lgkmcnt(2)
	v_mfma_f32_16x16x32_bf16 v[2:5], v[22:25], v[90:93], v[2:5]
	v_mfma_f32_16x16x32_bf16 v[6:9], v[38:41], v[90:93], v[6:9]
	s_waitcnt lgkmcnt(0)
	v_mfma_f32_16x16x32_bf16 v[2:5], v[26:29], v[94:97], v[2:5]
	v_mfma_f32_16x16x32_bf16 v[6:9], v[42:45], v[94:97], v[6:9]
	s_nop 3
	v_ashrrev_i32_e32 v11, 31, v0
	v_or_b32_e32 v10, v0, v140
	v_lshl_add_u64 v[12:13], v[10:11], 0, v[164:165]
	v_lshlrev_b64 v[12:13], 12, v[12:13]
	v_lshl_add_u64 v[12:13], v[162:163], 0, v[12:13]
	v_add_co_u32_e32 v14, vcc, s23, v12
	global_store_dword v[12:13], v2, off
	s_nop 0
	v_addc_co_u32_e32 v15, vcc, 0, v13, vcc
	v_add_co_u32_e32 v2, vcc, s20, v12
	global_store_dword v[14:15], v3, off offset:-4096
	global_store_dword v[14:15], v4, off
	v_addc_co_u32_e32 v3, vcc, 0, v13, vcc
	global_store_dword v[2:3], v5, off
	v_lshl_add_u64 v[2:3], v[10:11], 0, v[166:167]
	v_lshlrev_b64 v[2:3], 12, v[2:3]
	v_lshl_add_u64 v[2:3], v[162:163], 0, v[2:3]
	v_add_co_u32_e32 v4, vcc, s23, v2
	global_store_dword v[2:3], v6, off
	s_nop 0
	v_addc_co_u32_e32 v5, vcc, 0, v3, vcc
	v_add_co_u32_e32 v2, vcc, 0x3000, v2
	global_store_dword v[4:5], v7, off offset:-4096
	global_store_dword v[4:5], v8, off
	v_addc_co_u32_e32 v3, vcc, 0, v3, vcc
	global_store_dword v[2:3], v9, off
	s_waitcnt vmcnt(10)
	v_mov_b64_e32 v[8:9], v[102:103]
	v_mov_b64_e32 v[4:5], v[98:99]
	v_mov_b64_e32 v[10:11], v[104:105]
	v_mov_b64_e32 v[6:7], v[100:101]
	v_cmp_eq_u32_e32 vcc, s28, v149
	s_bitcmp1_b32 s28, 0
	s_cbranch_scc0 .Ls5_rot_q1
	v_mov_b64_e32 v[102:103], v[106:107]
	v_mov_b64_e32 v[98:99], v[110:111]
	v_mov_b64_e32 v[104:105], v[108:109]
	v_mov_b64_e32 v[100:101], v[112:113]
	s_branch .Ls5_rot_done
.Ls5_rot_q1:
	v_mov_b64_e32 v[102:103], v[214:215]
	v_mov_b64_e32 v[98:99], v[218:219]
	v_mov_b64_e32 v[104:105], v[216:217]
	v_mov_b64_e32 v[100:101], v[220:221]
.Ls5_rot_done:
	s_or_b64 s[2:3], vcc, s[2:3]
	s_andn2_b64 exec, exec, s[2:3]
	s_cbranch_execz .LBB0_106
.LBB0_100:
	s_add_i32 s20, s28, 3
	v_cmp_lt_u32_e32 vcc, s20, v149
	s_and_saveexec_b64 s[20:21], vcc
	s_cbranch_execz .LBB0_102
	s_add_i32 s50, s34, 16
	v_mov_b32_e32 v0, s50
	v_add_u32_e32 v2, -16, v210
	v_cndmask_b32_e64 v0, v2, v0, s[40:41]
	v_or_b32_e32 v2, v0, v205
	v_ashrrev_i32_e32 v3, 31, v2
	v_lshlrev_b64 v[2:3], 12, v[2:3]
	v_lshl_add_u64 v[2:3], v[156:157], 0, v[2:3]
	s_bitcmp1_b32 s28, 0
	s_cbranch_scc0 .Ls5_ld_q1
	global_load_dwordx4 v[110:113], v[2:3], off offset:16
	global_load_dwordx4 v[106:109], v[2:3], off
	s_branch .LBB0_102
.Ls5_ld_q1:
	global_load_dwordx4 v[218:221], v[2:3], off offset:16
	global_load_dwordx4 v[214:217], v[2:3], off
